# final RMSNorm phase: per-row loads (4 ssq partial loads + 4 row loads) issued together with counted vmcnt instead of 5 serialized load-wait rounds per row
# speedup vs baseline: 1.0211x; 1.0136x over previous
; __device__ __forceinline__ float bf_lo(unsigned w) { return __uint_as_float(w << 16); }
; __device__ __forceinline__ float bf_hi(unsigned w) { return __uint_as_float(w & 0xffff0000u); }
;     static __device__ __forceinline__ float rowsum(const float* ssq, int row, int np) {
;         const f32x4* p = (const f32x4*)(ssq + (size_t)row * np);
;         float s = 0.f;
;         for (int i = 0; i < np / 4; ++i) { const f32x4 v = p[i]; s += (v[0] + v[1]) + (v[2] + v[3]); }
;         return s;
;     }
; __device__ __forceinline__ void final_phase(const KP& p, unsigned char* ws) {
;     ...
;     for (int m = gw; m < T; m += NGW) {
;         const float rs = rsqrtf(Epi::rowsum(ssq, m, 16) * (1.0f / DM) + EPS);
;         const u32x2* xr = (const u32x2*)(xb + (size_t)m * DM) + lane;
;         f32x4* orow = (f32x4*)(p.out + (size_t)m * DM) + lane;
; #pragma unroll
;         for (int j = 0; j < 4; ++j) { const u32x2 w = xr[64 * j]; f32x4 v = (f32x4){bf_lo(w.x), bf_hi(w.x), bf_lo(w.y), bf_hi(w.y)}; v = v * rs * g[j]; orow[64 * j] = v; }
;     }
.LBB0_37:
	v_lshl_add_u64 v[26:27], v[20:21], 0, s[4:5]
	s_mov_b64 s[6:7], 0x700000
	v_lshl_add_u64 v[38:39], v[26:27], 0, s[6:7]
	v_lshl_add_u64 v[44:45], v[22:23], 0, s[4:5]
	v_add_u32_e32 v18, s38, v18
	global_load_dwordx4 v[26:29], v[38:39], off
	global_load_dwordx4 v[30:33], v[38:39], off offset:48
	global_load_dwordx4 v[34:37], v[38:39], off offset:32
	s_nop 0
	global_load_dwordx4 v[38:41], v[38:39], off offset:16
	global_load_dwordx2 v[46:47], v[44:45], off offset:-1024
	global_load_dwordx2 v[48:49], v[44:45], off offset:-512
	global_load_dwordx2 v[50:51], v[44:45], off
	s_nop 0
	global_load_dwordx2 v[44:45], v[44:45], off offset:512
	v_lshl_add_u64 v[20:21], v[20:21], 0, s[40:41]
	v_lshl_add_u64 v[22:23], v[22:23], 0, s[42:43]
	s_waitcnt vmcnt(4)
	v_mov_b32_e32 v42, v27
	v_mov_b32_e32 v43, v28
	v_mov_b32_e32 v27, v29
	v_mov_b32_e32 v28, v39
	v_mov_b32_e32 v29, v40
	v_mov_b32_e32 v39, v41
	v_pk_add_f32 v[26:27], v[42:43], v[26:27]
	v_pk_add_f32 v[28:29], v[28:29], v[38:39]
	v_add_f32_e32 v0, v26, v27
	v_pk_add_f32 v[28:29], v[28:29], v[28:29] op_sel:[0,1] op_sel_hi:[1,0]
	v_add_f32_e32 v26, 0, v0
	v_add_f32_e32 v34, v34, v35
	v_add_f32_e32 v36, v36, v37
	v_mov_b32_e32 v27, v30
	v_mov_b32_e32 v29, v31
	v_mov_b32_e32 v35, v32
	v_mov_b32_e32 v37, v33
	v_pk_add_f32 v[26:27], v[26:27], v[28:29]
	v_pk_add_f32 v[28:29], v[34:35], v[36:37]
	s_nop 0
	v_pk_add_f32 v[26:27], v[26:27], v[28:29]
	s_nop 0
	v_add_f32_e32 v0, v26, v27
	v_fmamk_f32 v0, v0, 0x3a800000, v217
	v_cmp_gt_f32_e32 vcc, s37, v0
	v_mul_f32_e32 v19, 0x4b800000, v0
	s_nop 0
	v_cndmask_b32_e32 v0, v0, v19, vcc
	v_rsq_f32_e32 v0, v0
	s_nop 0
	v_mul_f32_e32 v19, 0x45800000, v0
	v_cndmask_b32_e32 v0, v0, v19, vcc
	s_waitcnt vmcnt(3)
	s_nop 0
	v_lshlrev_b32_e32 v28, 16, v46
	v_and_b32_e32 v29, 0xffff0000, v46
	v_lshlrev_b32_e32 v26, 16, v47
	v_and_b32_e32 v27, 0xffff0000, v47
	v_pk_mul_f32 v[32:33], v[0:1], v[28:29] op_sel_hi:[0,1]
	v_pk_mul_f32 v[26:27], v[0:1], v[26:27] op_sel_hi:[0,1]
	v_pk_mul_f32 v[28:29], v[4:5], v[26:27]
	v_pk_mul_f32 v[26:27], v[2:3], v[32:33]
	global_store_dwordx4 v[24:25], v[26:29], off offset:-3072
	s_waitcnt vmcnt(3)
	s_nop 0
	v_lshlrev_b32_e32 v28, 16, v48
	v_and_b32_e32 v29, 0xffff0000, v48
	v_lshlrev_b32_e32 v26, 16, v49
	v_and_b32_e32 v27, 0xffff0000, v49
	v_pk_mul_f32 v[32:33], v[0:1], v[28:29] op_sel_hi:[0,1]
	v_pk_mul_f32 v[26:27], v[0:1], v[26:27] op_sel_hi:[0,1]
	v_pk_mul_f32 v[28:29], v[8:9], v[26:27]
	v_pk_mul_f32 v[26:27], v[6:7], v[32:33]
	global_store_dwordx4 v[24:25], v[26:29], off offset:-2048
	s_waitcnt vmcnt(3)
	s_nop 0
	v_lshlrev_b32_e32 v28, 16, v50
	v_and_b32_e32 v29, 0xffff0000, v50
	v_lshlrev_b32_e32 v26, 16, v51
	v_and_b32_e32 v27, 0xffff0000, v51
	v_pk_mul_f32 v[32:33], v[0:1], v[28:29] op_sel_hi:[0,1]
	v_pk_mul_f32 v[26:27], v[0:1], v[26:27] op_sel_hi:[0,1]
	v_pk_mul_f32 v[28:29], v[12:13], v[26:27]
	v_pk_mul_f32 v[26:27], v[10:11], v[32:33]
	global_store_dwordx4 v[24:25], v[26:29], off offset:-1024
	s_waitcnt vmcnt(3)
	s_nop 0
	v_lshlrev_b32_e32 v28, 16, v44
	v_and_b32_e32 v29, 0xffff0000, v44
	v_lshlrev_b32_e32 v26, 16, v45
	v_and_b32_e32 v27, 0xffff0000, v45
	v_pk_mul_f32 v[32:33], v[0:1], v[28:29] op_sel_hi:[0,1]
	v_pk_mul_f32 v[26:27], v[0:1], v[26:27] op_sel_hi:[0,1]
	v_pk_mul_f32 v[28:29], v[16:17], v[26:27]
	v_pk_mul_f32 v[26:27], v[14:15], v[32:33]
	global_store_dwordx4 v[24:25], v[26:29], off
	v_cmp_lt_i32_e32 vcc, s65, v18
	s_or_b64 s[46:47], vcc, s[46:47]
	v_lshl_add_u64 v[24:25], v[24:25], 0, s[44:45]
	s_andn2_b64 exec, exec, s[46:47]
	s_cbranch_execnz .LBB0_37
